# ln_router L0 router GEMV: packed-f32 v_pk_mul/v_pk_fma dot products with 3-expert-deep LDS read pipeline (fp32, reassociated sum)
# speedup vs baseline: 1.0046x; 1.0046x over previous
.Lr6_join:
	v_pk_add_f32 v[28:29], v[28:29], v[74:75] op_sel:[0,1] neg_lo:[0,1] neg_hi:[0,1]
	v_pk_add_f32 v[30:31], v[30:31], v[74:75] op_sel:[0,1] neg_lo:[0,1] neg_hi:[0,1]
	v_pk_mul_f32 v[28:29], v[28:29], v[76:77] op_sel_hi:[1,0]
	v_pk_mul_f32 v[30:31], v[30:31], v[76:77] op_sel_hi:[1,0]
	v_ashrrev_i32_e32 v49, 31, v48
	v_lshlrev_b64 v[82:83], 11, v[48:49]
	v_pk_add_f32 v[24:25], v[24:25], v[74:75] op_sel:[0,1] neg_lo:[0,1] neg_hi:[0,1]
	v_pk_add_f32 v[26:27], v[26:27], v[74:75] op_sel:[0,1] neg_lo:[0,1] neg_hi:[0,1]
	v_pk_mul_f32 v[24:25], v[24:25], v[76:77] op_sel_hi:[1,0]
	v_pk_mul_f32 v[26:27], v[26:27], v[76:77] op_sel_hi:[1,0]
	v_pk_add_f32 v[20:21], v[20:21], v[74:75] op_sel:[0,1] neg_lo:[0,1] neg_hi:[0,1]
	v_pk_add_f32 v[22:23], v[22:23], v[74:75] op_sel:[0,1] neg_lo:[0,1] neg_hi:[0,1]
	v_pk_mul_f32 v[20:21], v[20:21], v[76:77] op_sel_hi:[1,0]
	v_pk_mul_f32 v[22:23], v[22:23], v[76:77] op_sel_hi:[1,0]
	v_pk_add_f32 v[16:17], v[16:17], v[74:75] op_sel:[0,1] neg_lo:[0,1] neg_hi:[0,1]
	v_pk_add_f32 v[18:19], v[18:19], v[74:75] op_sel:[0,1] neg_lo:[0,1] neg_hi:[0,1]
	v_pk_mul_f32 v[16:17], v[16:17], v[76:77] op_sel_hi:[1,0]
	v_pk_mul_f32 v[18:19], v[18:19], v[76:77] op_sel_hi:[1,0]
	s_waitcnt vmcnt(4)
	v_pk_fma_f32 v[28:29], v[100:101], v[28:29], v[116:117]
	v_pk_add_f32 v[34:35], v[148:149], 1.0 op_sel_hi:[1,0]
	v_pk_fma_f32 v[30:31], v[102:103], v[30:31], v[118:119]
	v_pk_fma_f32 v[28:29], v[34:35], v[28:29], v[132:133]
	v_pk_add_f32 v[34:35], v[150:151], 1.0 op_sel_hi:[1,0]
	s_nop 0
	v_pk_fma_f32 v[30:31], v[30:31], v[34:35], v[134:135]
	v_lshl_add_u64 v[32:33], v[62:63], 0, v[82:83]
	v_cvt_pk_bf16_f32 v36, v28, v29
	v_cvt_pk_bf16_f32 v37, v30, v31
	global_store_dwordx2 v[32:33], v[36:37], off
	v_pk_fma_f32 v[24:25], v[104:105], v[24:25], v[120:121]
	v_pk_add_f32 v[34:35], v[152:153], 1.0 op_sel_hi:[1,0]
	v_pk_fma_f32 v[26:27], v[106:107], v[26:27], v[122:123]
	v_pk_fma_f32 v[24:25], v[34:35], v[24:25], v[136:137]
	v_pk_add_f32 v[34:35], v[154:155], 1.0 op_sel_hi:[1,0]
	s_nop 0
	v_pk_fma_f32 v[26:27], v[26:27], v[34:35], v[138:139]
	v_cvt_pk_bf16_f32 v36, v24, v25
	v_cvt_pk_bf16_f32 v37, v26, v27
	global_store_dwordx2 v[32:33], v[36:37], off offset:512
	v_pk_fma_f32 v[20:21], v[108:109], v[20:21], v[124:125]
	v_pk_add_f32 v[34:35], v[156:157], 1.0 op_sel_hi:[1,0]
	v_pk_fma_f32 v[22:23], v[110:111], v[22:23], v[126:127]
	v_pk_fma_f32 v[20:21], v[34:35], v[20:21], v[140:141]
	v_pk_add_f32 v[34:35], v[158:159], 1.0 op_sel_hi:[1,0]
	s_nop 0
	v_pk_fma_f32 v[22:23], v[22:23], v[34:35], v[142:143]
	v_cvt_pk_bf16_f32 v36, v20, v21
	v_cvt_pk_bf16_f32 v37, v22, v23
	global_store_dwordx2 v[32:33], v[36:37], off offset:1024
	v_pk_fma_f32 v[16:17], v[112:113], v[16:17], v[128:129]
	v_pk_add_f32 v[34:35], v[160:161], 1.0 op_sel_hi:[1,0]
	v_pk_fma_f32 v[18:19], v[114:115], v[18:19], v[130:131]
	v_pk_fma_f32 v[16:17], v[34:35], v[16:17], v[144:145]
	v_pk_add_f32 v[34:35], v[162:163], 1.0 op_sel_hi:[1,0]
	s_nop 0
	v_pk_fma_f32 v[18:19], v[18:19], v[34:35], v[146:147]
	v_cvt_pk_bf16_f32 v36, v16, v17
	v_cvt_pk_bf16_f32 v37, v18, v19
	global_store_dwordx2 v[32:33], v[36:37], off offset:1536
	ds_read_b128 v[100:103], v52
	ds_read_b128 v[104:107], v52 offset:1024
	ds_read_b128 v[108:111], v52 offset:2048
	ds_read_b128 v[112:115], v52 offset:3072
	ds_read_b128 v[116:119], v52 offset:4096
	ds_read_b128 v[120:123], v52 offset:5120
	ds_read_b128 v[124:127], v52 offset:6144
	ds_read_b128 v[128:131], v52 offset:7168
	ds_read_b128 v[132:135], v52 offset:8192
	ds_read_b128 v[136:139], v52 offset:9216
	ds_read_b128 v[140:143], v52 offset:10240
	ds_read_b128 v[144:147], v52 offset:11264
	s_waitcnt lgkmcnt(8)
	v_pk_mul_f32 v[148:149], v[28:29], v[100:101]
	v_pk_fma_f32 v[148:149], v[30:31], v[102:103], v[148:149]
	v_pk_fma_f32 v[148:149], v[24:25], v[104:105], v[148:149]
	v_pk_fma_f32 v[148:149], v[26:27], v[106:107], v[148:149]
	v_pk_fma_f32 v[148:149], v[20:21], v[108:109], v[148:149]
	v_pk_fma_f32 v[148:149], v[22:23], v[110:111], v[148:149]
	v_pk_fma_f32 v[148:149], v[16:17], v[112:113], v[148:149]
	v_pk_fma_f32 v[148:149], v[18:19], v[114:115], v[148:149]
	ds_read_b128 v[100:103], v52 offset:12288
	ds_read_b128 v[104:107], v52 offset:13312
	ds_read_b128 v[108:111], v52 offset:14336
	ds_read_b128 v[112:115], v52 offset:15360
	v_add_f32_e32 v32, v148, v149
	s_waitcnt lgkmcnt(8)
	v_pk_mul_f32 v[148:149], v[28:29], v[116:117]
	v_pk_fma_f32 v[148:149], v[30:31], v[118:119], v[148:149]
	v_pk_fma_f32 v[148:149], v[24:25], v[120:121], v[148:149]
	v_pk_fma_f32 v[148:149], v[26:27], v[122:123], v[148:149]
	v_pk_fma_f32 v[148:149], v[20:21], v[124:125], v[148:149]
	v_pk_fma_f32 v[148:149], v[22:23], v[126:127], v[148:149]
	v_pk_fma_f32 v[148:149], v[16:17], v[128:129], v[148:149]
	v_pk_fma_f32 v[148:149], v[18:19], v[130:131], v[148:149]
	ds_read_b128 v[116:119], v52 offset:16384
	ds_read_b128 v[120:123], v52 offset:17408
	ds_read_b128 v[124:127], v52 offset:18432
	ds_read_b128 v[128:131], v52 offset:19456
	v_add_f32_e32 v33, v148, v149
	s_waitcnt lgkmcnt(8)
	v_pk_mul_f32 v[148:149], v[28:29], v[132:133]
	v_pk_fma_f32 v[148:149], v[30:31], v[134:135], v[148:149]
	v_pk_fma_f32 v[148:149], v[24:25], v[136:137], v[148:149]
	v_pk_fma_f32 v[148:149], v[26:27], v[138:139], v[148:149]
	v_pk_fma_f32 v[148:149], v[20:21], v[140:141], v[148:149]
	v_pk_fma_f32 v[148:149], v[22:23], v[142:143], v[148:149]
	v_pk_fma_f32 v[148:149], v[16:17], v[144:145], v[148:149]
	v_pk_fma_f32 v[148:149], v[18:19], v[146:147], v[148:149]
	ds_read_b128 v[132:135], v52 offset:20480
	ds_read_b128 v[136:139], v52 offset:21504
	ds_read_b128 v[140:143], v52 offset:22528
	ds_read_b128 v[144:147], v52 offset:23552
	v_add_f32_e32 v34, v148, v149
	s_waitcnt lgkmcnt(8)
	v_pk_mul_f32 v[148:149], v[28:29], v[100:101]
	v_pk_fma_f32 v[148:149], v[30:31], v[102:103], v[148:149]
	v_pk_fma_f32 v[148:149], v[24:25], v[104:105], v[148:149]
	v_pk_fma_f32 v[148:149], v[26:27], v[106:107], v[148:149]
	v_pk_fma_f32 v[148:149], v[20:21], v[108:109], v[148:149]
	v_pk_fma_f32 v[148:149], v[22:23], v[110:111], v[148:149]
	v_pk_fma_f32 v[148:149], v[16:17], v[112:113], v[148:149]
	v_pk_fma_f32 v[148:149], v[18:19], v[114:115], v[148:149]
	ds_read_b128 v[100:103], v52 offset:24576
	ds_read_b128 v[104:107], v52 offset:25600
	ds_read_b128 v[108:111], v52 offset:26624
	ds_read_b128 v[112:115], v52 offset:27648
	v_add_f32_e32 v35, v148, v149
	s_waitcnt lgkmcnt(8)
	v_pk_mul_f32 v[148:149], v[28:29], v[116:117]
	v_pk_fma_f32 v[148:149], v[30:31], v[118:119], v[148:149]
	v_pk_fma_f32 v[148:149], v[24:25], v[120:121], v[148:149]
	v_pk_fma_f32 v[148:149], v[26:27], v[122:123], v[148:149]
	v_pk_fma_f32 v[148:149], v[20:21], v[124:125], v[148:149]
	v_pk_fma_f32 v[148:149], v[22:23], v[126:127], v[148:149]
	v_pk_fma_f32 v[148:149], v[16:17], v[128:129], v[148:149]
	v_pk_fma_f32 v[148:149], v[18:19], v[130:131], v[148:149]
	ds_read_b128 v[116:119], v52 offset:28672
	ds_read_b128 v[120:123], v52 offset:29696
	ds_read_b128 v[124:127], v52 offset:30720
	ds_read_b128 v[128:131], v52 offset:31744
	v_add_f32_e32 v36, v148, v149
	s_waitcnt lgkmcnt(8)
	v_pk_mul_f32 v[148:149], v[28:29], v[132:133]
	v_pk_fma_f32 v[148:149], v[30:31], v[134:135], v[148:149]
	v_pk_fma_f32 v[148:149], v[24:25], v[136:137], v[148:149]
	v_pk_fma_f32 v[148:149], v[26:27], v[138:139], v[148:149]
	v_pk_fma_f32 v[148:149], v[20:21], v[140:141], v[148:149]
	v_pk_fma_f32 v[148:149], v[22:23], v[142:143], v[148:149]
	v_pk_fma_f32 v[148:149], v[16:17], v[144:145], v[148:149]
	v_pk_fma_f32 v[148:149], v[18:19], v[146:147], v[148:149]
	ds_read_b128 v[132:135], v52 offset:32768
	ds_read_b128 v[136:139], v52 offset:33792
	ds_read_b128 v[140:143], v52 offset:34816
	ds_read_b128 v[144:147], v52 offset:35840
	v_add_f32_e32 v37, v148, v149
	s_waitcnt lgkmcnt(8)
	v_pk_mul_f32 v[148:149], v[28:29], v[100:101]
	v_pk_fma_f32 v[148:149], v[30:31], v[102:103], v[148:149]
	v_pk_fma_f32 v[148:149], v[24:25], v[104:105], v[148:149]
	v_pk_fma_f32 v[148:149], v[26:27], v[106:107], v[148:149]
	v_pk_fma_f32 v[148:149], v[20:21], v[108:109], v[148:149]
	v_pk_fma_f32 v[148:149], v[22:23], v[110:111], v[148:149]
	v_pk_fma_f32 v[148:149], v[16:17], v[112:113], v[148:149]
	v_pk_fma_f32 v[148:149], v[18:19], v[114:115], v[148:149]
	ds_read_b128 v[100:103], v52 offset:36864
	ds_read_b128 v[104:107], v52 offset:37888
	ds_read_b128 v[108:111], v52 offset:38912
	ds_read_b128 v[112:115], v52 offset:39936
	v_add_f32_e32 v46, v148, v149
	s_waitcnt lgkmcnt(8)
	v_pk_mul_f32 v[148:149], v[28:29], v[116:117]
	v_pk_fma_f32 v[148:149], v[30:31], v[118:119], v[148:149]
	v_pk_fma_f32 v[148:149], v[24:25], v[120:121], v[148:149]
	v_pk_fma_f32 v[148:149], v[26:27], v[122:123], v[148:149]
	v_pk_fma_f32 v[148:149], v[20:21], v[124:125], v[148:149]
	v_pk_fma_f32 v[148:149], v[22:23], v[126:127], v[148:149]
	v_pk_fma_f32 v[148:149], v[16:17], v[128:129], v[148:149]
	v_pk_fma_f32 v[148:149], v[18:19], v[130:131], v[148:149]
	ds_read_b128 v[116:119], v52 offset:40960
	ds_read_b128 v[120:123], v52 offset:41984
	ds_read_b128 v[124:127], v52 offset:43008
	ds_read_b128 v[128:131], v52 offset:44032
	v_add_f32_e32 v47, v148, v149
	s_waitcnt lgkmcnt(8)
	v_pk_mul_f32 v[148:149], v[28:29], v[132:133]
	v_pk_fma_f32 v[148:149], v[30:31], v[134:135], v[148:149]
	v_pk_fma_f32 v[148:149], v[24:25], v[136:137], v[148:149]
	v_pk_fma_f32 v[148:149], v[26:27], v[138:139], v[148:149]
	v_pk_fma_f32 v[148:149], v[20:21], v[140:141], v[148:149]
	v_pk_fma_f32 v[148:149], v[22:23], v[142:143], v[148:149]
	v_pk_fma_f32 v[148:149], v[16:17], v[144:145], v[148:149]
	v_pk_fma_f32 v[148:149], v[18:19], v[146:147], v[148:149]
	ds_read_b128 v[132:135], v52 offset:45056
	ds_read_b128 v[136:139], v52 offset:46080
	ds_read_b128 v[140:143], v52 offset:47104
	ds_read_b128 v[144:147], v52 offset:48128
	v_add_f32_e32 v73, v148, v149
	s_waitcnt lgkmcnt(8)
	v_pk_mul_f32 v[148:149], v[28:29], v[100:101]
	v_pk_fma_f32 v[148:149], v[30:31], v[102:103], v[148:149]
	v_pk_fma_f32 v[148:149], v[24:25], v[104:105], v[148:149]
	v_pk_fma_f32 v[148:149], v[26:27], v[106:107], v[148:149]
	v_pk_fma_f32 v[148:149], v[20:21], v[108:109], v[148:149]
	v_pk_fma_f32 v[148:149], v[22:23], v[110:111], v[148:149]
	v_pk_fma_f32 v[148:149], v[16:17], v[112:113], v[148:149]
	v_pk_fma_f32 v[148:149], v[18:19], v[114:115], v[148:149]
	ds_read_b128 v[100:103], v52 offset:49152
	ds_read_b128 v[104:107], v52 offset:50176
	ds_read_b128 v[108:111], v52 offset:51200
	ds_read_b128 v[112:115], v52 offset:52224
	v_add_f32_e32 v74, v148, v149
	s_waitcnt lgkmcnt(8)
	v_pk_mul_f32 v[148:149], v[28:29], v[116:117]
	v_pk_fma_f32 v[148:149], v[30:31], v[118:119], v[148:149]
	v_pk_fma_f32 v[148:149], v[24:25], v[120:121], v[148:149]
	v_pk_fma_f32 v[148:149], v[26:27], v[122:123], v[148:149]
	v_pk_fma_f32 v[148:149], v[20:21], v[124:125], v[148:149]
	v_pk_fma_f32 v[148:149], v[22:23], v[126:127], v[148:149]
	v_pk_fma_f32 v[148:149], v[16:17], v[128:129], v[148:149]
	v_pk_fma_f32 v[148:149], v[18:19], v[130:131], v[148:149]
	ds_read_b128 v[116:119], v52 offset:53248
	ds_read_b128 v[120:123], v52 offset:54272
	ds_read_b128 v[124:127], v52 offset:55296
	ds_read_b128 v[128:131], v52 offset:56320
	v_add_f32_e32 v75, v148, v149
	s_waitcnt lgkmcnt(8)
	v_pk_mul_f32 v[148:149], v[28:29], v[132:133]
	v_pk_fma_f32 v[148:149], v[30:31], v[134:135], v[148:149]
	v_pk_fma_f32 v[148:149], v[24:25], v[136:137], v[148:149]
	v_pk_fma_f32 v[148:149], v[26:27], v[138:139], v[148:149]
	v_pk_fma_f32 v[148:149], v[20:21], v[140:141], v[148:149]
	v_pk_fma_f32 v[148:149], v[22:23], v[142:143], v[148:149]
	v_pk_fma_f32 v[148:149], v[16:17], v[144:145], v[148:149]
	v_pk_fma_f32 v[148:149], v[18:19], v[146:147], v[148:149]
	ds_read_b128 v[132:135], v52 offset:57344
	ds_read_b128 v[136:139], v52 offset:58368
	ds_read_b128 v[140:143], v52 offset:59392
	ds_read_b128 v[144:147], v52 offset:60416
	v_add_f32_e32 v76, v148, v149
	s_waitcnt lgkmcnt(8)
	v_pk_mul_f32 v[148:149], v[28:29], v[100:101]
	v_pk_fma_f32 v[148:149], v[30:31], v[102:103], v[148:149]
	v_pk_fma_f32 v[148:149], v[24:25], v[104:105], v[148:149]
	v_pk_fma_f32 v[148:149], v[26:27], v[106:107], v[148:149]
	v_pk_fma_f32 v[148:149], v[20:21], v[108:109], v[148:149]
	v_pk_fma_f32 v[148:149], v[22:23], v[110:111], v[148:149]
	v_pk_fma_f32 v[148:149], v[16:17], v[112:113], v[148:149]
	v_pk_fma_f32 v[148:149], v[18:19], v[114:115], v[148:149]
	ds_read_b128 v[100:103], v52 offset:61440
	ds_read_b128 v[104:107], v52 offset:62464
	ds_read_b128 v[108:111], v52 offset:63488
	ds_read_b128 v[112:115], v52 offset:64512
	v_add_f32_e32 v82, v148, v149
	s_waitcnt lgkmcnt(8)
	v_pk_mul_f32 v[148:149], v[28:29], v[116:117]
	v_pk_fma_f32 v[148:149], v[30:31], v[118:119], v[148:149]
	v_pk_fma_f32 v[148:149], v[24:25], v[120:121], v[148:149]
	v_pk_fma_f32 v[148:149], v[26:27], v[122:123], v[148:149]
	v_pk_fma_f32 v[148:149], v[20:21], v[124:125], v[148:149]
	v_pk_fma_f32 v[148:149], v[22:23], v[126:127], v[148:149]
	v_pk_fma_f32 v[148:149], v[16:17], v[128:129], v[148:149]
	v_pk_fma_f32 v[148:149], v[18:19], v[130:131], v[148:149]
	v_add_f32_e32 v83, v148, v149
	s_waitcnt lgkmcnt(4)
	v_pk_mul_f32 v[148:149], v[28:29], v[132:133]
	v_pk_fma_f32 v[148:149], v[30:31], v[134:135], v[148:149]
	v_pk_fma_f32 v[148:149], v[24:25], v[136:137], v[148:149]
	v_pk_fma_f32 v[148:149], v[26:27], v[138:139], v[148:149]
	v_pk_fma_f32 v[148:149], v[20:21], v[140:141], v[148:149]
	v_pk_fma_f32 v[148:149], v[22:23], v[142:143], v[148:149]
	v_pk_fma_f32 v[148:149], v[16:17], v[144:145], v[148:149]
	v_pk_fma_f32 v[148:149], v[18:19], v[146:147], v[148:149]
	v_add_f32_e32 v87, v148, v149
	s_waitcnt lgkmcnt(0)
	v_pk_mul_f32 v[148:149], v[28:29], v[100:101]
	v_pk_fma_f32 v[148:149], v[30:31], v[102:103], v[148:149]
	v_pk_fma_f32 v[148:149], v[24:25], v[104:105], v[148:149]
	v_pk_fma_f32 v[148:149], v[26:27], v[106:107], v[148:149]
	v_pk_fma_f32 v[148:149], v[20:21], v[108:109], v[148:149]
	v_pk_fma_f32 v[148:149], v[22:23], v[110:111], v[148:149]
	v_pk_fma_f32 v[148:149], v[16:17], v[112:113], v[148:149]
	v_pk_fma_f32 v[148:149], v[18:19], v[114:115], v[148:149]
	v_add_f32_e32 v16, v148, v149
	v_cndmask_b32_e64 v18, v32, v73, s[34:35]
	v_mov_b32_e32 v19, v18
	s_nop 1
	v_permlane32_swap_b32_e32 v18, v19
	v_cndmask_b32_e64 v18, v18, v19, s[34:35]
	v_cndmask_b32_e64 v19, v33, v74, s[34:35]
	v_mov_b32_e32 v20, v19
	s_nop 1
	v_permlane32_swap_b32_e32 v19, v20
	v_cndmask_b32_e64 v19, v19, v20, s[34:35]
	v_cndmask_b32_e64 v20, v34, v75, s[34:35]
	v_mov_b32_e32 v21, v20
	s_nop 1
	v_permlane32_swap_b32_e32 v20, v21
	v_cndmask_b32_e64 v20, v20, v21, s[34:35]
	v_cndmask_b32_e64 v21, v35, v76, s[34:35]
	v_mov_b32_e32 v22, v21
	s_nop 1
	v_permlane32_swap_b32_e32 v21, v22
	v_cndmask_b32_e64 v21, v21, v22, s[34:35]
	v_cndmask_b32_e64 v22, v36, v82, s[34:35]
	v_mov_b32_e32 v23, v22
	s_nop 1
	v_permlane32_swap_b32_e32 v22, v23
	v_cndmask_b32_e64 v17, v73, v32, s[34:35]
	v_cndmask_b32_e64 v22, v22, v23, s[34:35]
	v_cndmask_b32_e64 v23, v37, v83, s[34:35]
	v_add_f32_e32 v17, v17, v18
	v_cndmask_b32_e64 v18, v74, v33, s[34:35]
	v_mov_b32_e32 v24, v23
	v_add_f32_e32 v18, v18, v19
	v_cndmask_b32_e64 v19, v75, v34, s[34:35]
	v_permlane32_swap_b32_e32 v23, v24
	v_add_f32_e32 v19, v19, v20
	v_cndmask_b32_e64 v20, v76, v35, s[34:35]
	v_cndmask_b32_e64 v23, v23, v24, s[34:35]
	v_cndmask_b32_e64 v24, v46, v87, s[34:35]
	v_add_f32_e32 v20, v20, v21
	v_cndmask_b32_e64 v21, v82, v36, s[34:35]
	v_mov_b32_e32 v25, v24
	v_add_f32_e32 v21, v21, v22
	v_cndmask_b32_e64 v22, v83, v37, s[34:35]
	v_permlane32_swap_b32_e32 v24, v25
	v_add_f32_e32 v22, v22, v23
	v_cndmask_b32_e64 v23, v87, v46, s[34:35]
	v_cndmask_b32_e64 v24, v24, v25, s[34:35]
	v_add_f32_e32 v23, v23, v24
	v_cndmask_b32_e64 v24, v16, v47, s[34:35]
	v_cndmask_b32_e64 v16, v47, v16, s[34:35]
	v_mov_b32_e32 v25, v16
	s_nop 1
	v_permlane32_swap_b32_e32 v16, v25
	v_cndmask_b32_e64 v16, v16, v25, s[34:35]
	v_add_f32_e32 v16, v24, v16
	v_cndmask_b32_e64 v24, v21, v17, s[4:5]
	v_cndmask_b32_e64 v17, v17, v21, s[4:5]
	v_mov_b32_e32 v21, v17
	s_nop 1
	v_permlane16_swap_b32_e32 v17, v21
	v_cndmask_b32_e64 v17, v17, v21, s[4:5]
	v_cndmask_b32_e64 v21, v22, v18, s[4:5]
	v_cndmask_b32_e64 v18, v18, v22, s[4:5]
	v_mov_b32_e32 v22, v18
	s_nop 1
	v_permlane16_swap_b32_e32 v18, v22
	v_cndmask_b32_e64 v18, v18, v22, s[4:5]
	v_add_f32_e32 v18, v21, v18
	v_cndmask_b32_e64 v21, v23, v19, s[4:5]
	v_cndmask_b32_e64 v19, v19, v23, s[4:5]
	v_mov_b32_e32 v22, v19
	s_nop 1
	v_permlane16_swap_b32_e32 v19, v22
	v_cndmask_b32_e64 v19, v19, v22, s[4:5]
	v_add_f32_e32 v19, v21, v19
	v_cndmask_b32_e64 v21, v16, v20, s[4:5]
	v_cndmask_b32_e64 v16, v20, v16, s[4:5]
	v_mov_b32_e32 v20, v16
	s_nop 1
	v_permlane16_swap_b32_e32 v16, v20
	v_cndmask_b32_e64 v16, v16, v20, s[4:5]
	v_add_f32_e32 v17, v24, v17
	v_add_f32_e32 v16, v21, v16
	v_cndmask_b32_e64 v20, v17, v19, s[6:7]
	v_cndmask_b32_e64 v21, v18, v16, s[6:7]
	ds_bpermute_b32 v20, v77, v20
	ds_bpermute_b32 v21, v77, v21
	v_cndmask_b32_e64 v17, v19, v17, s[6:7]
	v_cndmask_b32_e64 v16, v16, v18, s[6:7]
	s_mov_b32 s2, 0x3fb8aa3b
	s_waitcnt lgkmcnt(1)
	v_add_f32_e32 v17, v17, v20
	s_waitcnt lgkmcnt(0)
	v_add_f32_e32 v16, v16, v21
	v_cndmask_b32_e64 v18, v17, v16, s[8:9]
	ds_bpermute_b32 v18, v84, v18
	v_cndmask_b32_e64 v16, v16, v17, s[8:9]
	s_waitcnt lgkmcnt(0)
	v_add_f32_e32 v16, v16, v18
	ds_bpermute_b32 v17, v85, v16
	s_waitcnt lgkmcnt(0)
	v_add_f32_e32 v16, v16, v17
	ds_bpermute_b32 v17, v86, v16
	s_waitcnt lgkmcnt(0)
	v_add_f32_e32 v16, v16, v17
	ds_bpermute_b32 v17, v77, v16
	s_waitcnt lgkmcnt(0)
	v_max_f32_e32 v17, v17, v17
	v_max_f32_e32 v17, v16, v17
	ds_bpermute_b32 v18, v84, v17
	s_waitcnt lgkmcnt(0)
	v_max_f32_e32 v18, v18, v18
	v_max_f32_e32 v17, v17, v18
	v_mov_b32_e32 v18, v17
	s_nop 1
	v_permlane16_swap_b32_e32 v17, v18
	v_max_f32_e32 v18, v18, v18
	v_max_f32_e32 v17, v17, v17
	v_max_f32_e32 v17, v17, v18
	v_mov_b32_e32 v18, v17
	s_nop 1
	v_permlane32_swap_b32_e32 v17, v18
	v_max_f32_e32 v18, v18, v18
	v_max_f32_e32 v17, v17, v17
	v_max_f32_e32 v17, v17, v18
	v_sub_f32_e32 v16, v16, v17
	v_mul_f32_e32 v17, 0x3fb8aa3b, v16
	v_fma_f32 v18, v16, s2, -v17
	v_rndne_f32_e32 v19, v17
	v_fmac_f32_e32 v18, 0x32a5705f, v16
	v_sub_f32_e32 v17, v17, v19
	v_add_f32_e32 v17, v17, v18
	v_exp_f32_e32 v17, v17
	v_cvt_i32_f32_e32 v18, v19
	s_mov_b32 s2, 0xc2ce8ed0
	v_cmp_ngt_f32_e32 vcc, s2, v16
	s_mov_b32 s2, 0x42b17218
	v_ldexp_f32 v17, v17, v18
	v_cndmask_b32_e32 v17, 0, v17, vcc
	v_cmp_nlt_f32_e32 vcc, s2, v16
	s_nop 1
	v_cndmask_b32_e32 v16, v53, v17, vcc
	ds_bpermute_b32 v17, v77, v16
	s_waitcnt lgkmcnt(0)
	v_add_f32_e32 v17, v16, v17
	ds_bpermute_b32 v18, v84, v17
	s_waitcnt lgkmcnt(0)
	v_add_f32_e32 v17, v17, v18
	v_mov_b32_e32 v18, v17
	s_nop 1
	v_permlane16_swap_b32_e32 v17, v18
	v_add_f32_e32 v17, v17, v18
	v_mov_b32_e32 v18, v17
	s_nop 1
	v_permlane32_swap_b32_e32 v17, v18
	s_and_saveexec_b64 s[2:3], s[0:1]
	s_cbranch_execz .LBB0_840
	v_add_f32_e32 v17, v17, v18
	v_div_scale_f32 v18, s[18:19], v17, v17, v16
	v_rcp_f32_e32 v19, v18
	v_div_scale_f32 v20, vcc, v16, v17, v16
	v_fma_f32 v21, -v18, v19, 1.0
	v_fmac_f32_e32 v19, v21, v19
	v_mul_f32_e32 v21, v20, v19
	v_fma_f32 v22, -v18, v21, v20
	v_fmac_f32_e32 v21, v22, v19
	v_fma_f32 v18, -v18, v21, v20
	v_div_fmas_f32 v18, v18, v19, v21
	v_div_fixup_f32 v18, v18, v17, v16
	v_lshlrev_b64 v[16:17], 6, v[48:49]
	v_lshl_add_u64 v[16:17], v[60:61], 0, v[16:17]
	global_store_dword v[16:17], v18, off
